# attention tile loop: last K fragment of each 32-key half read early into spare registers (one fewer exposed LDS wait per half)
# speedup vs baseline: 1.0060x; 1.0060x over previous
; #define LAS __attribute__((address_space(3)))
; DI f32x16 mfma32(bf16x8 a, bf16x8 b, f32x16 c) { return __builtin_amdgcn_mfma_f32_32x32x16_bf16(a, b, c, 0, 0, 0); }
; #define AT_LOAD(tl_) do { _Pragma("unroll") for (int i_ = 0; i_ < 2; ++i_) { const bf16_t* b_ = proj + (size_t)(kt0 + (tl_) * 64 + skey + 32 * i_) * PP + 64 * kvh + sdc; \
;     rk[i_] = *(const u32x4*)(b_ + C_K); rv[i_] = *(const u32x4*)(b_ + C_V); } } while (0)
; #define AT_STORE(buf_) do { _Pragma("unroll") for (int i_ = 0; i_ < 2; ++i_) { *(u32x4*)(Ks + (buf_) * 64 * 72 + (skey + 32 * i_) * 72 + sdc) = rk[i_]; \
;     *(u32x4*)(Vs + (buf_) * 64 * 72 + (skey + 32 * i_) * 72 + sdc) = rv[i_]; } } while (0)
; DI void attn_unit(const Params& p, int unit, unsigned char* lds) {
;     ...
;   AT_LOAD(0); AT_STORE(0); __syncthreads();
;   const int gi = (lane >> 4) & 1, qq = (lane & 15) >> 2, pp = lane & 3;
;   const int troff = (4 * hh + qq) * 72 + 16 * gi + 4 * pp;
;   for (int tl = 0; tl < 64; ++tl) {
;     { const int tn_ = tl + 1 < 64 ? tl + 1 : 63; AT_LOAD(tn_); }
;     asm volatile("" ::: "memory"); __builtin_amdgcn_sched_barrier(0);
;     const bf16_t* k_ = Ks + (tl & 1) * 64 * 72; const bf16_t* v_ = Vs + (tl & 1) * 64 * 72;
; #pragma unroll
;     for (int kt = 0; kt < 2; ++kt) {
;       f32x16 Sx[2];
;       f32x16 zero16;
; #pragma unroll
;       for (int i = 0; i < 16; ++i) zero16[i] = 0.f;
; #pragma unroll
;       for (int ks = 0; ks < 4; ++ks) {
;         const bf16x8 kf = *(const bf16x8*)(k_ + (32 * kt + r) * 72 + 16 * ks + 8 * hh);
; #pragma unroll
;         for (int g = 0; g < 2; ++g) Sx[g] = mfma32(kf, Qf[g][ks], ks == 0 ? zero16 : Sx[g]);
;       }
;       bf16x8 vf[2][2];
; #pragma unroll
;       for (int s = 0; s < 2; ++s)
; #pragma unroll
;         for (int dt = 0; dt < 2; ++dt) {
;           const bf16_t* vb_ = v_ + (32 * kt + 16 * s) * 72 + 32 * dt + troff;
;           const s16x4 lo = __builtin_amdgcn_ds_read_tr16_b64_v4i16((LAS s16x4*)(vb_));
;           const s16x4 hi = __builtin_amdgcn_ds_read_tr16_b64_v4i16((LAS s16x4*)(vb_ + 8 * 72));
;           vf[s][dt] = __builtin_shufflevector(lo, hi, 0, 1, 2, 3, 4, 5, 6, 7);
;         }
; #pragma unroll
;       for (int g = 0; g < 2; ++g) {
;         float pv[16];
; #pragma unroll
;         for (int i = 0; i < 16; ++i) { pv[i] = __builtin_amdgcn_exp2f(Sx[g][i]); lsum[g] += pv[i]; }
.LBB0_99:
	s_add_i32 s5, s4, 64
	global_load_dwordx4 v[128:131], v[238:239], off
	global_load_dwordx4 v[132:135], v[238:239], off offset:256
	global_load_dwordx4 v[136:139], v[240:241], off
	global_load_dwordx4 v[140:143], v[240:241], off offset:256
	v_lshl_add_u64 v[238:239], v[238:239], 0, s[6:7]
	v_lshl_add_u64 v[240:241], v[240:241], 0, s[6:7]
	s_and_b32 s2, s4, 64
	s_mulk_i32 s2, 0x90
	v_add_u32_e32 v205, s2, v160
	ds_read_b128 v[64:67], v205
	ds_read_b128 v[144:147], v205 offset:32
	ds_read_b128 v[242:245], v205 offset:96
	v_add_u32_e32 v153, s2, v165
	s_and_b32 s2, s5, 64
	s_mulk_i32 s2, 0x90
	s_waitcnt lgkmcnt(2)
	v_mfma_f32_32x32x16_bf16 v[80:95], v[64:67], v[116:119], 0
	s_cmpk_eq_i32 s5, 0xfc0
	s_mov_b32 s4, s5
	v_mfma_f32_32x32x16_bf16 v[64:79], v[64:67], v[124:127], 0
	s_waitcnt lgkmcnt(1)
	v_mfma_f32_32x32x16_bf16 v[80:95], v[144:147], v[108:111], v[80:95]
	v_mfma_f32_32x32x16_bf16 v[64:79], v[144:147], v[120:123], v[64:79]
	ds_read_b128 v[144:147], v205 offset:64
	s_waitcnt lgkmcnt(0)
	v_mfma_f32_32x32x16_bf16 v[80:95], v[144:147], v[100:103], v[80:95]
	v_mfma_f32_32x32x16_bf16 v[64:79], v[144:147], v[112:115], v[64:79]
	v_mfma_f32_32x32x16_bf16 v[80:95], v[242:245], v[96:99], v[80:95]
	v_mfma_f32_32x32x16_bf16 v[64:79], v[242:245], v[104:107], v[64:79]
	ds_read_b64_tr_b16 v[206:207], v153 offset:18432
	ds_read_b64_tr_b16 v[208:209], v153 offset:19584
	ds_read_b64_tr_b16 v[210:211], v153 offset:18496
	ds_read_b64_tr_b16 v[212:213], v153 offset:19648
	ds_read_b64_tr_b16 v[144:145], v153 offset:20736
	ds_read_b64_tr_b16 v[146:147], v153 offset:21888
	ds_read_b64_tr_b16 v[148:149], v153 offset:20800
	ds_read_b64_tr_b16 v[150:151], v153 offset:21952
	s_nop 2
	v_exp_f32_e32 v157, v80
	v_exp_f32_e32 v81, v81
	v_exp_f32_e32 v215, v82
	v_exp_f32_e32 v83, v83
	v_exp_f32_e32 v217, v84
	v_exp_f32_e32 v85, v85
	v_exp_f32_e32 v219, v86
	v_exp_f32_e32 v87, v87
	v_exp_f32_e32 v156, v64
	v_exp_f32_e32 v80, v65
	v_exp_f32_e32 v214, v66
	v_exp_f32_e32 v82, v67
	v_cvt_pk_bf16_f32 v64, v157, v81
	v_cvt_pk_bf16_f32 v65, v215, v83
	v_cvt_pk_bf16_f32 v66, v217, v85
	v_cvt_pk_bf16_f32 v67, v219, v87
	v_exp_f32_e32 v216, v68
	v_exp_f32_e32 v84, v69
	s_waitcnt lgkmcnt(6)
	v_mfma_f32_32x32x16_bf16 v[48:63], v[206:209], v[64:67], v[48:63]
	v_exp_f32_e32 v218, v70
	v_exp_f32_e32 v86, v71
	v_exp_f32_e32 v221, v88
	v_exp_f32_e32 v220, v72
	v_exp_f32_e32 v89, v89
	v_exp_f32_e32 v88, v73
	v_exp_f32_e32 v159, v90
	s_waitcnt lgkmcnt(4)
	v_mfma_f32_32x32x16_bf16 v[32:47], v[210:213], v[64:67], v[32:47]
	v_add_f32_e64 v64, v154, v156
	v_add_f32_e64 v65, v155, v157
	v_cvt_pk_bf16_f32 v66, v216, v84
	v_add_f32_e64 v64, v80, v64
	v_add_f32_e64 v65, v81, v65
	v_cvt_pk_bf16_f32 v67, v218, v86
	v_add_f32_e32 v64, v214, v64
	v_add_f32_e32 v65, v215, v65
	v_exp_f32_e32 v171, v91
	v_add_f32_e32 v64, v82, v64
	v_add_f32_e32 v65, v83, v65
	v_exp_f32_e32 v169, v92
	v_add_f32_e32 v64, v216, v64
	v_add_f32_e32 v65, v217, v65
	v_exp_f32_e32 v175, v93
	v_add_f32_e32 v64, v84, v64
	v_add_f32_e32 v65, v85, v65
	v_exp_f32_e32 v173, v94
	v_add_f32_e32 v64, v218, v64
	v_add_f32_e32 v65, v219, v65
	v_exp_f32_e32 v177, v95
	v_add_f32_e32 v64, v86, v64
	v_add_f32_e32 v65, v87, v65
	v_cvt_pk_bf16_f32 v152, v221, v89
	v_add_f32_e32 v64, v220, v64
	v_add_f32_e32 v65, v221, v65
	v_exp_f32_e32 v158, v74
	v_add_f32_e32 v178, v88, v64
	v_add_f32_e32 v179, v89, v65
	v_cvt_pk_bf16_f32 v64, v156, v80
	v_cvt_pk_bf16_f32 v65, v214, v82
	v_exp_f32_e32 v170, v75
	v_exp_f32_e32 v168, v76
	v_mfma_f32_32x32x16_bf16 v[16:31], v[206:209], v[64:67], v[16:31]
	ds_read_b128 v[206:209], v205 offset:4640
	v_exp_f32_e32 v174, v77
	v_exp_f32_e32 v172, v78
	v_exp_f32_e32 v176, v79
	v_cvt_pk_bf16_f32 v156, v220, v88
	v_cvt_pk_bf16_f32 v154, v169, v175
	v_cvt_pk_bf16_f32 v155, v173, v177
	v_mfma_f32_32x32x16_bf16 v[0:15], v[210:213], v[64:67], v[0:15]
	ds_read_b128 v[64:67], v205 offset:4608
	ds_read_b128 v[242:245], v205 offset:4704
	v_cvt_pk_bf16_f32 v157, v158, v170
	s_waitcnt lgkmcnt(1)
	v_mfma_f32_32x32x16_bf16 v[80:95], v[64:67], v[116:119], 0
	v_mfma_f32_32x32x16_bf16 v[64:79], v[64:67], v[124:127], 0
	v_mfma_f32_32x32x16_bf16 v[80:95], v[206:209], v[108:111], v[80:95]
	v_mfma_f32_32x32x16_bf16 v[64:79], v[206:209], v[120:123], v[64:79]
	ds_read_b128 v[206:209], v205 offset:4672
	s_waitcnt lgkmcnt(0)
; #define LAS __attribute__((address_space(3)))
; DI unsigned pk2(float lo, float hi) { f32x2 v = {lo, hi}; bfv2 b = __builtin_convertvector(v, bfv2); return __builtin_bit_cast(unsigned, b); }
; DI f32x16 mfma32(bf16x8 a, bf16x8 b, f32x16 c) { return __builtin_amdgcn_mfma_f32_32x32x16_bf16(a, b, c, 0, 0, 0); }
; #define AT_STORE(buf_) do { _Pragma("unroll") for (int i_ = 0; i_ < 2; ++i_) { *(u32x4*)(Ks + (buf_) * 64 * 72 + (skey + 32 * i_) * 72 + sdc) = rk[i_]; \
;     *(u32x4*)(Vs + (buf_) * 64 * 72 + (skey + 32 * i_) * 72 + sdc) = rv[i_]; } } while (0)
; DI void attn_unit(const Params& p, int unit, unsigned char* lds) {
;     ...
;       for (int ks = 0; ks < 4; ++ks) {
;         const bf16x8 kf = *(const bf16x8*)(k_ + (32 * kt + r) * 72 + 16 * ks + 8 * hh);
; #pragma unroll
;         for (int g = 0; g < 2; ++g) Sx[g] = mfma32(kf, Qf[g][ks], ks == 0 ? zero16 : Sx[g]);
;       }
;       bf16x8 vf[2][2];
; #pragma unroll
;       for (int s = 0; s < 2; ++s)
; #pragma unroll
;         for (int dt = 0; dt < 2; ++dt) {
;           const bf16_t* vb_ = v_ + (32 * kt + 16 * s) * 72 + 32 * dt + troff;
;           const s16x4 lo = __builtin_amdgcn_ds_read_tr16_b64_v4i16((LAS s16x4*)(vb_));
;           const s16x4 hi = __builtin_amdgcn_ds_read_tr16_b64_v4i16((LAS s16x4*)(vb_ + 8 * 72));
;           vf[s][dt] = __builtin_shufflevector(lo, hi, 0, 1, 2, 3, 4, 5, 6, 7);
;         }
; #pragma unroll
;       for (int g = 0; g < 2; ++g) {
;         float pv[16];
; #pragma unroll
;         for (int i = 0; i < 16; ++i) { pv[i] = __builtin_amdgcn_exp2f(Sx[g][i]); lsum[g] += pv[i]; }
;         bf16x8 Pb[2];
; #pragma unroll
;         for (int s = 0; s < 2; ++s) {
;           const u32x4 w = {pk2(pv[8 * s], pv[8 * s + 1]), pk2(pv[8 * s + 2], pv[8 * s + 3]), pk2(pv[8 * s + 4], pv[8 * s + 5]), pk2(pv[8 * s + 6], pv[8 * s + 7])};
;           Pb[s] = __builtin_bit_cast(bf16x8, w);
;         }
; #pragma unroll
;         for (int s = 0; s < 2; ++s)
; #pragma unroll
;           for (int dt = 0; dt < 2; ++dt) O[dt][g] = mfma32(vf[s][dt], Pb[s], O[dt][g]);
;       }
;     }
;     if (tl + 1 < 64) AT_STORE((tl + 1) & 1);
;     __syncthreads();
	v_mfma_f32_32x32x16_bf16 v[80:95], v[206:209], v[100:103], v[80:95]
	v_mfma_f32_32x32x16_bf16 v[64:79], v[206:209], v[112:115], v[64:79]
	v_mfma_f32_32x32x16_bf16 v[80:95], v[242:245], v[96:99], v[80:95]
	v_mfma_f32_32x32x16_bf16 v[64:79], v[242:245], v[104:107], v[64:79]
	ds_read_b64_tr_b16 v[206:207], v153 offset:23040
	ds_read_b64_tr_b16 v[208:209], v153 offset:24192
	ds_read_b64_tr_b16 v[210:211], v153 offset:23104
	ds_read_b64_tr_b16 v[212:213], v153 offset:24256
	ds_read_b64_tr_b16 v[214:215], v153 offset:25344
	ds_read_b64_tr_b16 v[216:217], v153 offset:26496
	ds_read_b64_tr_b16 v[218:219], v153 offset:25408
	ds_read_b64_tr_b16 v[220:221], v153 offset:26560
	s_nop 2
	v_exp_f32_e32 v223, v80
	v_exp_f32_e32 v81, v81
	v_exp_f32_e32 v225, v82
	v_cvt_pk_bf16_f32 v153, v159, v171
	v_exp_f32_e32 v83, v83
	v_exp_f32_e32 v227, v84
	v_exp_f32_e32 v222, v64
	v_exp_f32_e32 v80, v65
	v_add_f32_e32 v64, v158, v178
	v_add_f32_e32 v65, v159, v179
	v_exp_f32_e32 v224, v66
	v_add_f32_e32 v64, v170, v64
	v_add_f32_e32 v65, v171, v65
	v_exp_f32_e32 v82, v67
	v_add_f32_e32 v64, v168, v64
	v_add_f32_e32 v65, v169, v65
	v_mfma_f32_32x32x16_bf16 v[48:63], v[144:147], v[152:155], v[48:63]
	v_add_f32_e64 v64, v174, v64
	v_add_f32_e64 v65, v175, v65
	v_cvt_pk_bf16_f32 v158, v168, v174
	v_add_f32_e64 v64, v172, v64
	v_add_f32_e64 v65, v173, v65
	v_cvt_pk_bf16_f32 v159, v172, v176
	v_exp_f32_e32 v226, v68
	v_exp_f32_e32 v85, v85
	v_exp_f32_e32 v84, v69
	v_mfma_f32_32x32x16_bf16 v[32:47], v[148:151], v[152:155], v[32:47]
	v_add_f32_e64 v152, v176, v64
	v_add_f32_e64 v153, v177, v65
	v_exp_f32_e32 v229, v86
	v_exp_f32_e32 v87, v87
	v_exp_f32_e32 v228, v70
	v_exp_f32_e32 v86, v71
	v_exp_f32_e32 v231, v88
	v_exp_f32_e32 v230, v72
	v_mfma_f32_32x32x16_bf16 v[16:31], v[144:147], v[156:159], v[16:31]
	v_add_f32_e64 v144, v152, v222
	v_add_f32_e64 v145, v153, v223
	v_exp_f32_e32 v89, v89
	v_add_f32_e32 v144, v80, v144
	v_add_f32_e32 v145, v81, v145
	v_exp_f32_e32 v88, v73
	v_add_f32_e32 v144, v224, v144
	v_add_f32_e32 v145, v225, v145
	v_exp_f32_e32 v233, v90
	v_add_f32_e32 v144, v82, v144
	v_add_f32_e32 v145, v83, v145
	v_mfma_f32_32x32x16_bf16 v[0:15], v[148:151], v[156:159], v[0:15]
	v_add_f32_e64 v144, v226, v144
	v_add_f32_e64 v145, v227, v145
	v_cvt_pk_bf16_f32 v64, v223, v81
	v_add_f32_e64 v68, v84, v144
	v_add_f32_e64 v69, v85, v145
	v_cvt_pk_bf16_f32 v65, v225, v83
	v_cvt_pk_bf16_f32 v66, v227, v85
	v_exp_f32_e32 v232, v74
	v_add_f32_e32 v68, v228, v68
	v_add_f32_e32 v69, v229, v69
	v_cvt_pk_bf16_f32 v67, v229, v87
	v_exp_f32_e32 v91, v91
	v_exp_f32_e32 v90, v75
	v_add_f32_e32 v68, v86, v68
	v_add_f32_e32 v69, v87, v69
	s_waitcnt lgkmcnt(6)
	v_mfma_f32_32x32x16_bf16 v[48:63], v[206:209], v[64:67], v[48:63]
	v_exp_f32_e32 v235, v92
	v_exp_f32_e32 v234, v76
	v_add_f32_e32 v68, v230, v68
	v_add_f32_e32 v69, v231, v69
	v_exp_f32_e32 v93, v93
	v_exp_f32_e32 v92, v77
	v_add_f32_e32 v68, v88, v68
	v_add_f32_e32 v69, v89, v69
	v_exp_f32_e32 v237, v94
	s_waitcnt lgkmcnt(4)
	v_mfma_f32_32x32x16_bf16 v[32:47], v[210:213], v[64:67], v[32:47]
	v_cvt_pk_bf16_f32 v64, v222, v80
	v_cvt_pk_bf16_f32 v65, v224, v82
	v_cvt_pk_bf16_f32 v66, v226, v84
	v_cvt_pk_bf16_f32 v67, v228, v86
	v_exp_f32_e32 v95, v95
	v_exp_f32_e32 v236, v78
	v_add_f32_e32 v68, v232, v68
	v_add_f32_e32 v69, v233, v69
	v_mfma_f32_32x32x16_bf16 v[16:31], v[206:209], v[64:67], v[16:31]
	v_exp_f32_e32 v94, v79
	v_add_f32_e32 v68, v90, v68
	v_add_f32_e32 v69, v91, v69
	v_cvt_pk_bf16_f32 v70, v235, v93
	v_add_f32_e32 v68, v234, v68
	v_add_f32_e32 v69, v235, v69
	v_cvt_pk_bf16_f32 v71, v237, v95
	v_add_f32_e32 v68, v92, v68
	v_add_f32_e32 v69, v93, v69
	v_mfma_f32_32x32x16_bf16 v[0:15], v[210:213], v[64:67], v[0:15]
	v_add_f32_e64 v72, v236, v68
	v_add_f32_e64 v73, v237, v69
	v_cvt_pk_bf16_f32 v68, v231, v89
	v_cvt_pk_bf16_f32 v69, v233, v91
	v_add_f32_e64 v154, v94, v72
	v_add_f32_e64 v155, v95, v73
	v_add_u32_e32 v64, s2, v204
	s_waitcnt vmcnt(3)
	ds_write_b128 v64, v[128:131]
	s_waitcnt vmcnt(2)
	ds_write_b128 v64, v[132:135] offset:18432
	s_waitcnt vmcnt(1)
	ds_write_b128 v64, v[136:139] offset:4608
	s_waitcnt vmcnt(0)
	ds_write_b128 v64, v[140:143] offset:23040
	s_waitcnt lgkmcnt(0)
	v_mfma_f32_32x32x16_bf16 v[48:63], v[214:217], v[68:71], v[48:63]
	s_barrier
	v_mfma_f32_32x32x16_bf16 v[32:47], v[218:221], v[68:71], v[32:47]
	v_cvt_pk_bf16_f32 v68, v230, v88
	v_cvt_pk_bf16_f32 v69, v232, v90
	v_cvt_pk_bf16_f32 v70, v234, v92
	v_cvt_pk_bf16_f32 v71, v236, v94
	s_nop 1
	v_mfma_f32_32x32x16_bf16 v[16:31], v[214:217], v[68:71], v[16:31]
	v_mfma_f32_32x32x16_bf16 v[0:15], v[218:221], v[68:71], v[0:15]
	s_cbranch_scc0 .LBB0_99
; #define LAS __attribute__((address_space(3)))
; DI unsigned pk2(float lo, float hi) { f32x2 v = {lo, hi}; bfv2 b = __builtin_convertvector(v, bfv2); return __builtin_bit_cast(unsigned, b); }
; DI f32x16 mfma32(bf16x8 a, bf16x8 b, f32x16 c) { return __builtin_amdgcn_mfma_f32_32x32x16_bf16(a, b, c, 0, 0, 0); }
; DI void attn_unit(const Params& p, int unit, unsigned char* lds) {
;     ...
;     const bf16_t* k_ = Ks + (tl & 1) * 64 * 72; const bf16_t* v_ = Vs + (tl & 1) * 64 * 72;
; #pragma unroll
;     for (int kt = 0; kt < 2; ++kt) {
;       f32x16 Sx[2];
;       f32x16 zero16;
; #pragma unroll
;       for (int i = 0; i < 16; ++i) zero16[i] = 0.f;
; #pragma unroll
;       for (int ks = 0; ks < 4; ++ks) {
;         const bf16x8 kf = *(const bf16x8*)(k_ + (32 * kt + r) * 72 + 16 * ks + 8 * hh);
; #pragma unroll
;         for (int g = 0; g < 2; ++g) Sx[g] = mfma32(kf, Qf[g][ks], ks == 0 ? zero16 : Sx[g]);
;       }
;       bf16x8 vf[2][2];
; #pragma unroll
;       for (int s = 0; s < 2; ++s)
; #pragma unroll
;         for (int dt = 0; dt < 2; ++dt) {
;           const bf16_t* vb_ = v_ + (32 * kt + 16 * s) * 72 + 32 * dt + troff;
;           const s16x4 lo = __builtin_amdgcn_ds_read_tr16_b64_v4i16((LAS s16x4*)(vb_));
;           const s16x4 hi = __builtin_amdgcn_ds_read_tr16_b64_v4i16((LAS s16x4*)(vb_ + 8 * 72));
;           vf[s][dt] = __builtin_shufflevector(lo, hi, 0, 1, 2, 3, 4, 5, 6, 7);
;         }
; #pragma unroll
;       for (int g = 0; g < 2; ++g) {
;         float pv[16];
; #pragma unroll
;         for (int i = 0; i < 16; ++i) { pv[i] = __builtin_amdgcn_exp2f(Sx[g][i]); lsum[g] += pv[i]; }
;         bf16x8 Pb[2];
; #pragma unroll
;         for (int s = 0; s < 2; ++s) {
;           const u32x4 w = {pk2(pv[8 * s], pv[8 * s + 1]), pk2(pv[8 * s + 2], pv[8 * s + 3]), pk2(pv[8 * s + 4], pv[8 * s + 5]), pk2(pv[8 * s + 6], pv[8 * s + 7])};
;           Pb[s] = __builtin_bit_cast(bf16x8, w);
;         }
; #pragma unroll
;         for (int s = 0; s < 2; ++s)
; #pragma unroll
;           for (int dt = 0; dt < 2; ++dt) O[dt][g] = mfma32(vf[s][dt], Pb[s], O[dt][g]);
;       }
;     }
;     if (tl + 1 < 64) AT_STORE((tl + 1) & 1);
;     __syncthreads();
;   }
;     ...
;   const int pcol = kvc == 0 ? A_V : (kvc == 1 ? A_Z : (kvc == 2 ? B_V : D_X));
	ds_read_b128 v[64:67], v160 offset:9216
	ds_read_b128 v[128:131], v160 offset:9248
	s_cmp_lt_i32 s34, 1
	s_mov_b64 s[8:9], 0x100
	s_waitcnt lgkmcnt(1)
	v_mfma_f32_32x32x16_bf16 v[80:95], v[64:67], v[116:119], 0
	v_mfma_f32_32x32x16_bf16 v[64:79], v[64:67], v[124:127], 0
	s_waitcnt lgkmcnt(0)
	v_mfma_f32_32x32x16_bf16 v[80:95], v[128:131], v[108:111], v[80:95]
	v_mfma_f32_32x32x16_bf16 v[64:79], v[128:131], v[120:123], v[64:79]
	ds_read_b128 v[128:131], v160 offset:9280
	s_waitcnt lgkmcnt(0)
	v_mfma_f32_32x32x16_bf16 v[80:95], v[128:131], v[100:103], v[80:95]
	v_mfma_f32_32x32x16_bf16 v[64:79], v[128:131], v[112:115], v[64:79]
	ds_read_b128 v[128:131], v160 offset:9312
	ds_read_b64_tr_b16 v[168:169], v165 offset:27648
	ds_read_b64_tr_b16 v[170:171], v165 offset:28800
	ds_read_b64_tr_b16 v[172:173], v165 offset:27712
	ds_read_b64_tr_b16 v[174:175], v165 offset:28864
	ds_read_b64_tr_b16 v[176:177], v165 offset:29952
	ds_read_b64_tr_b16 v[178:179], v165 offset:31104
	ds_read_b64_tr_b16 v[204:205], v165 offset:30016
	ds_read_b64_tr_b16 v[206:207], v165 offset:31168
	s_waitcnt lgkmcnt(8)
	v_mfma_f32_32x32x16_bf16 v[64:79], v[128:131], v[104:107], v[64:79]
	v_mfma_f32_32x32x16_bf16 v[80:95], v[128:131], v[96:99], v[80:95]
	s_nop 10
	v_exp_f32_e32 v128, v64
	v_exp_f32_e32 v129, v65
	v_exp_f32_e32 v130, v66
	v_exp_f32_e32 v131, v67
	v_exp_f32_e32 v132, v68
	v_exp_f32_e32 v133, v69
	v_exp_f32_e32 v134, v70
	v_exp_f32_e32 v135, v71
	v_exp_f32_e32 v144, v80
	v_exp_f32_e32 v145, v81
	v_exp_f32_e32 v146, v82
	v_exp_f32_e32 v147, v83
	v_exp_f32_e32 v148, v84
	v_exp_f32_e32 v149, v85
	v_exp_f32_e32 v150, v86
	v_exp_f32_e32 v151, v87
	v_cvt_pk_bf16_f32 v64, v128, v129
	v_cvt_pk_bf16_f32 v65, v130, v131
	v_cvt_pk_bf16_f32 v66, v132, v133
	v_cvt_pk_bf16_f32 v67, v134, v135
	v_cvt_pk_bf16_f32 v80, v144, v145
	v_cvt_pk_bf16_f32 v81, v146, v147
	v_cvt_pk_bf16_f32 v82, v148, v149
	v_cvt_pk_bf16_f32 v83, v150, v151
	s_waitcnt lgkmcnt(6)
	v_mfma_f32_32x32x16_bf16 v[16:31], v[168:171], v[64:67], v[16:31]
	v_exp_f32_e32 v152, v88
	v_exp_f32_e32 v153, v89
	v_exp_f32_e32 v156, v90
	v_exp_f32_e32 v157, v91
	v_exp_f32_e32 v158, v92
	v_exp_f32_e32 v159, v93
	v_exp_f32_e32 v166, v94
	s_waitcnt lgkmcnt(4)
	v_mfma_f32_32x32x16_bf16 v[0:15], v[172:175], v[64:67], v[0:15]
	ds_read_b128 v[64:67], v160 offset:13824
	v_exp_f32_e32 v167, v95
	v_cvt_pk_bf16_f32 v84, v152, v153
	v_cvt_pk_bf16_f32 v85, v156, v157
	v_cvt_pk_bf16_f32 v86, v158, v159
	v_cvt_pk_bf16_f32 v87, v166, v167
	v_exp_f32_e32 v136, v72
	v_mfma_f32_32x32x16_bf16 v[48:63], v[168:171], v[80:83], v[48:63]
	v_exp_f32_e32 v137, v73
	v_exp_f32_e32 v138, v74
	v_exp_f32_e32 v139, v75
	v_exp_f32_e32 v140, v76
	v_exp_f32_e32 v141, v77
	v_exp_f32_e32 v142, v78
	v_exp_f32_e32 v143, v79
	v_mfma_f32_32x32x16_bf16 v[32:47], v[172:175], v[80:83], v[32:47]
	v_cvt_pk_bf16_f32 v68, v136, v137
	v_cvt_pk_bf16_f32 v69, v138, v139
	v_cvt_pk_bf16_f32 v70, v140, v141
	v_cvt_pk_bf16_f32 v71, v142, v143
	s_waitcnt lgkmcnt(3)
	v_mfma_f32_32x32x16_bf16 v[48:63], v[176:179], v[84:87], v[48:63]
	s_waitcnt lgkmcnt(1)
	v_mfma_f32_32x32x16_bf16 v[32:47], v[204:207], v[84:87], v[32:47]
	s_waitcnt lgkmcnt(0)
	v_mfma_f32_32x32x16_bf16 v[80:95], v[64:67], v[116:119], 0
	ds_read_b128 v[116:119], v160 offset:13856
	v_mfma_f32_32x32x16_bf16 v[16:31], v[176:179], v[68:71], v[16:31]
	v_mfma_f32_32x32x16_bf16 v[0:15], v[204:207], v[68:71], v[0:15]
	v_mfma_f32_32x32x16_bf16 v[64:79], v[64:67], v[124:127], 0
	s_waitcnt lgkmcnt(0)
	v_mfma_f32_32x32x16_bf16 v[80:95], v[116:119], v[108:111], v[80:95]
	ds_read_b128 v[108:111], v160 offset:13888
	v_mfma_f32_32x32x16_bf16 v[64:79], v[116:119], v[120:123], v[64:79]
	s_waitcnt lgkmcnt(0)
	v_mfma_f32_32x32x16_bf16 v[80:95], v[108:111], v[100:103], v[80:95]
	ds_read_b128 v[100:103], v160 offset:13920
	v_mfma_f32_32x32x16_bf16 v[64:79], v[108:111], v[112:115], v[64:79]
	s_waitcnt lgkmcnt(0)
	v_mfma_f32_32x32x16_bf16 v[80:95], v[100:103], v[96:99], v[80:95]
	v_mfma_f32_32x32x16_bf16 v[64:79], v[100:103], v[104:107], v[64:79]
	s_nop 10
	v_exp_f32_e32 v80, v80
	v_exp_f32_e32 v81, v81
	v_exp_f32_e32 v82, v82
	v_exp_f32_e32 v83, v83
	v_exp_f32_e32 v84, v84
	v_exp_f32_e32 v85, v85
	v_exp_f32_e32 v86, v86
	v_exp_f32_e32 v87, v87
	ds_read_b64_tr_b16 v[108:109], v165 offset:32256
	ds_read_b64_tr_b16 v[110:111], v165 offset:33408
	ds_read_b64_tr_b16 v[104:105], v165 offset:32320
	ds_read_b64_tr_b16 v[106:107], v165 offset:33472
	ds_read_b64_tr_b16 v[96:97], v165 offset:34560
	ds_read_b64_tr_b16 v[98:99], v165 offset:35712
	ds_read_b64_tr_b16 v[100:101], v165 offset:34624
	ds_read_b64_tr_b16 v[102:103], v165 offset:35776
	v_cvt_pk_bf16_f32 v112, v80, v81
	v_cvt_pk_bf16_f32 v113, v82, v83
	v_cvt_pk_bf16_f32 v114, v84, v85
	v_cvt_pk_bf16_f32 v115, v86, v87
	v_exp_f32_e32 v68, v68
	v_exp_f32_e32 v69, v69
	s_waitcnt lgkmcnt(6)
	v_mfma_f32_32x32x16_bf16 v[48:63], v[108:111], v[112:115], v[48:63]
	v_exp_f32_e32 v70, v70
	v_exp_f32_e32 v71, v71
	v_exp_f32_e32 v88, v88
	v_exp_f32_e32 v89, v89
	v_exp_f32_e32 v90, v90
	v_exp_f32_e32 v91, v91
	v_exp_f32_e32 v92, v92
	s_waitcnt lgkmcnt(4)
	v_mfma_f32_32x32x16_bf16 v[32:47], v[104:107], v[112:115], v[32:47]
	v_exp_f32_e32 v112, v64
	v_exp_f32_e32 v113, v65
	v_exp_f32_e32 v114, v66
	v_exp_f32_e32 v115, v67
	v_cvt_pk_bf16_f32 v66, v68, v69
	v_cvt_pk_bf16_f32 v64, v112, v113
	v_cvt_pk_bf16_f32 v67, v70, v71
	v_cvt_pk_bf16_f32 v65, v114, v115
	v_exp_f32_e32 v93, v93
	v_exp_f32_e32 v94, v94
	v_mfma_f32_32x32x16_bf16 v[16:31], v[108:111], v[64:67], v[16:31]
	v_exp_f32_e32 v95, v95
	v_exp_f32_e32 v72, v72
	v_exp_f32_e32 v73, v73
	v_exp_f32_e32 v74, v74
	v_exp_f32_e32 v75, v75
	v_exp_f32_e32 v76, v76
	v_exp_f32_e32 v77, v77
	v_mfma_f32_32x32x16_bf16 v[0:15], v[104:107], v[64:67], v[0:15]
	v_exp_f32_e32 v78, v78
	v_exp_f32_e32 v79, v79
	v_cvt_pk_bf16_f32 v116, v88, v89
	v_cvt_pk_bf16_f32 v117, v90, v91
	v_cvt_pk_bf16_f32 v118, v92, v93
	v_cvt_pk_bf16_f32 v119, v94, v95
	s_waitcnt lgkmcnt(0)
	s_barrier
	v_mfma_f32_32x32x16_bf16 v[48:63], v[96:99], v[116:119], v[48:63]
	v_mfma_f32_32x32x16_bf16 v[32:47], v[100:103], v[116:119], v[32:47]
	v_cvt_pk_bf16_f32 v116, v72, v73
	v_cvt_pk_bf16_f32 v117, v74, v75
	v_cvt_pk_bf16_f32 v118, v76, v77
	v_cvt_pk_bf16_f32 v119, v78, v79
	s_nop 1
	v_mfma_f32_32x32x16_bf16 v[16:31], v[96:99], v[116:119], v[16:31]
	v_mfma_f32_32x32x16_bf16 v[0:15], v[100:103], v[116:119], v[0:15]
	s_cbranch_scc1 .LBB0_105
	s_cmp_lg_u32 s34, 1
	s_mov_b64 s[4:5], -1
	s_cbranch_scc0 .LBB0_103
	s_cmp_eq_u32 s34, 2
	s_cselect_b32 s84, s45, 0xa00
	s_mov_b64 s[4:5], 0
	s_mov_b64 s[8:9], s[84:85]
